# up-GEMM tile order: WGM 8 -> 4 (4 row panels x 8 column tiles per XCD round; A panels can stay L2-resident across rounds), on top of v40
# speedup vs baseline: 1.0005x; 1.0005x over previous
;     __host__ __device__ bool next(int i, Unit& u) const {
;         const long L = (long)i * G + c; if (L >= nwg) return false;
;         int wgid = (int)L; { const int q = nwg / NXCD, r = nwg % NXCD, xcd = wgid % NXCD, off = wgid / NXCD; wgid = (xcd < r ? xcd * (q + 1) : r * (q + 1) + (xcd - r) * q) + off; }
;         const int nig = WGM * nN, gid = wgid / nig, fm = gid * WGM, gsz = (nM - fm) < WGM ? (nM - fm) : WGM;
;         u.pm = fm + ((wgid % nig) % gsz); u.pn = (wgid % nig) / gsz; return true;
;     }
; template <class Epi, class Sched, bool ALIGN_EPI = false, bool SP2 = false>
; __device__ __forceinline__ void gemm_phase(PG8_LAS unsigned char* lds, const Gemm g, const Sched& S, const Epi& E) {
;     const int tid = otid(), wid = __builtin_amdgcn_readfirstlane(tid >> 6), lane = tid & 63, wr = wid >> 2, wc = wid & 3, fr = lane & 15, fq = lane >> 4;
;     const int K = g.K, nt = K / BK;
;     unsigned voffA[2], voffB[2];
; #pragma unroll
;     for (int i = 0; i < 2; ++i) { int R, C; stage_rc(tid * 16 + i * 8192, R, C); const int Rb = Epi::PERM ? ((R & ~31) + perm32(R & 31)) : R;
;         voffA[i] = (unsigned)(R * g.lda + C) * 2u; voffB[i] = (unsigned)(Rb * K + C) * 2u; }
;     const size_t kstep = (size_t)(BK * 2);
;     const size_t hstepB = (size_t)HALF * K * 2, hstepA = (size_t)HALF * g.lda * 2;
;     const size_t tstepA = 2 * hstepA, tstepB = 2 * hstepB;
;     const unsigned ldsw = (unsigned)wid * 1024u;
;     const int aoff = lds_byte(wr * 64 + fr, fq * 8), boff = lds_byte(wc * 32 + fr, fq * 8);
;     ...
;     Unit cur, nxt; int ui = 0;
;     if (!S.next(0, cur)) return;
;     f32x4 acc[2][2][4][2];
; #pragma unroll
;     for (int a = 0; a < 2; ++a)
; #pragma unroll
;         for (int b = 0; b < 2; ++b)
; #pragma unroll
;             for (int m = 0; m < 4; ++m)
; #pragma unroll
;                 for (int n = 0; n < 2; ++n) acc[a][b][m][n] = (f32x4){0.f, 0.f, 0.f, 0.f};
;     bf16x8 At[4][2], B0[2][2], B1[2][2];
;     const char* cA = (const char*)g.A + (size_t)cur.pm * tstepA; const char* cB = (const char*)g.Bt + (size_t)cur.pn * tstepB;
;     S.a_ready(cur);
;     if constexpr (SP2) {
;         PG8_STAGE(PG8_SB(0, 0), cB, voffB); PG8_STAGE(PG8_SB(0, 1), cB + hstepB, voffB); PG8_STAGE(PG8_SA(0, 0), cA, voffA); PG8_STAGE(PG8_SA(0, 1), cA + hstepA, voffA);
;         if (wr == 1) PG8_BAR;
;         PG8_WAIT_V(2); PG8_BAR;
.LBB0_434:
	s_andn2_b64 vcc, exec, s[8:9]
	s_cbranch_vccnz .LBB0_451
	s_and_b64 s[4:5], exec, s[60:61]
	s_movk_i32 s2, 0x108
	s_cselect_b32 s2, s2, 0x100
	s_mov_b32 s4, s36
	s_mul_i32 s34, s2, 22
	v_mov_b32_e32 v8, v163
	s_cmp_ge_i32 s4, s34
	v_readfirstlane_b32 s9, v8
	s_cbranch_scc1 .LBB0_451
	s_waitcnt vmcnt(0)
	v_lshlrev_b32_e32 v0, 4, v8
	v_add_u32_e32 v1, 0x2000, v0
	s_waitcnt lgkmcnt(0)
	v_ashrrev_i32_e32 v2, 31, v1
	v_lshrrev_b32_e32 v2, 22, v2
	v_add_u32_e32 v2, v1, v2
	v_ashrrev_i32_e32 v9, 10, v2
	v_mul_i32_i24_e32 v2, 0x400, v9
	v_sub_u32_e32 v1, v1, v2
	v_lshrrev_b32_e32 v2, 4, v1
	v_bitop3_b32 v1, v2, v1, 32 bitop3:0x6c
	v_ashrrev_i32_e32 v2, 31, v1
	v_lshrrev_b32_e32 v2, 26, v2
	v_add_u32_e32 v2, v1, v2
	v_lshlrev_b32_e32 v3, 3, v9
	v_ashrrev_i32_e32 v10, 6, v2
	v_and_b32_e32 v3, -16, v3
	v_add_u32_e32 v3, v10, v3
	v_and_b32_e32 v4, 3, v10
	s_mov_b32 s8, 0x1fffe0
	v_lshrrev_b32_e32 v5, 2, v3
	v_lshlrev_b32_e32 v6, 1, v3
	v_and_b32_e32 v2, 0xc0, v2
	v_and_or_b32 v4, v3, s8, v4
	v_and_b32_e32 v5, 4, v5
	v_and_b32_e32 v6, 24, v6
	v_sub_u32_e32 v1, v1, v2
	v_or3_b32 v4, v4, v5, v6
	v_lshlrev_b32_e32 v5, 5, v9
	v_ashrrev_i16_sdwa v1, v246, sext(v1) dst_sel:DWORD dst_unused:UNUSED_PAD src0_sel:DWORD src1_sel:BYTE_0
	v_and_b32_e32 v5, 32, v5
	v_bfe_i32 v11, v1, 0, 16
	v_add_lshl_u32 v1, v5, v11, 1
	v_lshl_add_u32 v128, v4, 11, v1
	v_lshl_add_u32 v130, v3, 11, v1
	v_bfe_i32 v1, v8, 27, 1
	v_lshrrev_b32_e32 v1, 22, v1
	v_add_u32_e32 v1, v0, v1
	v_and_b32_e32 v1, 0xfffffc00, v1
	v_sub_u32_e32 v0, v0, v1
	v_lshrrev_b32_e32 v1, 4, v0
	v_bitop3_b32 v1, v1, v0, 32 bitop3:0x6c
	v_ashrrev_i32_e32 v0, 31, v0
	v_lshrrev_b32_e32 v0, 26, v0
	v_add_u32_e32 v0, v1, v0
	v_ashrrev_i32_e32 v12, 6, v0
	v_ashrrev_i32_e32 v0, 31, v8
	v_lshrrev_b32_e32 v0, 26, v0
	s_lshl_b64 s[6:7], s[62:63], 1
	v_add_u32_e32 v0, v8, v0
	s_add_u32 s5, s54, s6
	v_ashrrev_i32_e32 v13, 6, v0
	s_addc_u32 s6, s55, s7
	v_lshlrev_b32_e32 v0, 3, v13
	s_add_u32 s5, s5, 0xc00000
	v_and_b32_e32 v0, -16, v0
	s_addc_u32 s6, s6, 0
	v_add_u32_e32 v0, v12, v0
	v_and_b32_e32 v2, 3, v12
	s_ashr_i32 s17, s4, 31
	v_and_or_b32 v2, v0, s8, v2
	s_lshr_b32 s8, s17, 29
	s_add_i32 s8, s4, s8
	s_ashr_i32 s13, s9, 6
	s_lshr_b32 s16, s34, 3
	s_ashr_i32 s10, s8, 3
	s_and_b32 s8, s8, -8
	s_ashr_i32 s12, s9, 8
	s_lshl_b32 s7, s13, 10
	s_sub_i32 s8, s4, s8
	s_or_b32 s18, s16, 1
	s_cmp_lt_i32 s8, 0
	s_cselect_b32 s11, s18, s16
	s_mul_i32 s8, s11, s8
	v_lshrrev_b32_e32 v3, 2, v0
	v_lshlrev_b32_e32 v4, 1, v0
	s_add_i32 s8, s8, s10
	v_and_b32_e32 v3, 4, v3
	v_and_b32_e32 v4, 24, v4
	s_mul_hi_i32 s10, s8, 0x2e8ba2e9
	v_or3_b32 v2, v2, v3, v4
	v_mul_i32_i24_e32 v4, 64, v12
	s_lshr_b32 s11, s10, 31
	s_ashr_i32 s10, s10, 4
	v_sub_u32_e32 v1, v1, v4
	s_add_i32 s10, s10, s11
	v_lshlrev_b32_e32 v3, 5, v13
	v_ashrrev_i16_sdwa v1, v246, sext(v1) dst_sel:DWORD dst_unused:UNUSED_PAD src0_sel:DWORD src1_sel:BYTE_0
	s_lshl_b32 s14, s10, 2
	v_and_b32_e32 v3, 32, v3
	v_bfe_i32 v14, v1, 0, 16
	s_sub_i32 s11, s2, s14
	v_add_lshl_u32 v1, v3, v14, 1
	s_min_i32 s15, s11, 4
	v_lshl_add_u32 v132, v0, 11, v1
	v_cvt_f32_i32_e32 v0, s15
	s_mulk_i32 s10, 0x58
	s_sub_i32 s19, s8, s10
	v_lshl_add_u32 v144, v2, 11, v1
	v_cvt_f32_i32_e32 v1, s19
	v_rcp_iflag_f32_e32 v2, v0
	s_xor_b32 s8, s19, s15
	s_ashr_i32 s8, s8, 30
	s_or_b32 s8, s8, 1
	v_mul_f32_e32 v2, v1, v2
	v_trunc_f32_e32 v2, v2
	v_fma_f32 v1, -v2, v0, v1
	v_cvt_i32_f32_e32 v2, v2
	v_cmp_ge_f32_e64 s[10:11], |v1|, |v0|
	s_and_b64 s[10:11], s[10:11], exec
	s_cselect_b32 s8, s8, 0
	v_readfirstlane_b32 s10, v2
	s_add_i32 s8, s10, s8
	s_mul_i32 s10, s8, s15
	s_sub_i32 s10, s19, s10
	s_sext_i32_i16 s10, s10
	s_add_i32 s62, s14, s10
	s_ashr_i32 s63, s62, 31
	s_bfe_i64 s[14:15], s[8:9], 0x100000
	s_lshl_b64 s[10:11], s[62:63], 19
	s_lshl_b64 s[14:15], s[14:15], 19
	s_add_u32 s64, s5, s14
	s_addc_u32 s65, s6, s15
	s_add_i32 s19, s7, 0
	s_add_i32 m0, s19, 0x10000
	s_load_dword s37, s[26:27], 0x0
	global_load_lds_dwordx4 v144, s[64:65]
	s_add_i32 m0, s19, 0x12000
	s_add_u32 s14, s64, 0x40000
	global_load_lds_dwordx4 v128, s[64:65]
	s_addc_u32 s15, s65, 0
	s_add_i32 m0, s19, 0x14000
	v_mov_b32_e32 v129, v145
	global_load_lds_dwordx4 v144, s[14:15]
	s_add_i32 m0, s19, 0x16000
	s_add_u32 s66, s56, s10
	s_addc_u32 s67, s57, s11
	s_add_i32 s24, s19, 0x2000
	global_load_lds_dwordx4 v128, s[14:15]
	s_mov_b32 m0, s19
	s_add_u32 s10, s66, 0x40000
	global_load_lds_dwordx4 v132, s[66:67]
	s_mov_b32 m0, s24
	s_addc_u32 s11, s67, 0
	s_add_i32 s25, s19, 0x4000
	global_load_lds_dwordx4 v130, s[66:67]
	s_mov_b32 m0, s25
	s_add_i32 s31, s19, 0x6000
	global_load_lds_dwordx4 v132, s[10:11]
	s_mov_b32 m0, s31
	v_mov_b32_e32 v133, v145
	global_load_lds_dwordx4 v130, s[10:11]
	v_mov_b32_e32 v131, v145
	s_cmp_eq_u32 s12, 1
	v_lshl_add_u64 v[6:7], s[64:65], 0, v[144:145]
	v_lshl_add_u64 v[4:5], s[64:65], 0, v[128:129]
	v_lshl_add_u64 v[0:1], s[66:67], 0, v[132:133]
	s_cselect_b64 s[10:11], -1, 0
	s_cmp_lg_u32 s12, 1
	v_lshl_add_u64 v[2:3], s[66:67], 0, v[130:131]
	s_cbranch_scc1 .LBB0_438
	s_barrier

; #define PG8_STAGE(bufoff, gbase, voff) do { _Pragma("unroll") for (int _i = 0; _i < 2; ++_i) \
;         __builtin_amdgcn_global_load_lds((const unsigned*)((const char*)(gbase) + (voff)[_i]), (PG8_LAS unsigned*)(lds + (bufoff) + ldsw + _i * 8192), 16, 0, 0); } while (0)
; #define PG8_LDA(dst, b, h) do { _Pragma("unroll") for (int m = 0; m < 4; ++m) _Pragma("unroll") for (int k = 0; k < 2; ++k) dst[m][k] = *(const PG8_LAS bf16x8*)(lds + PG8_SA(b, h) + aoff + m * 2048 + k * 1024); } while (0)
; #define PG8_LDB(dst, b, h) do { _Pragma("unroll") for (int n = 0; n < 2; ++n) _Pragma("unroll") for (int k = 0; k < 2; ++k) dst[n][k] = *(const PG8_LAS bf16x8*)(lds + PG8_SB(b, h) + boff + n * 2048 + k * 1024); } while (0)
; #define PG8_BAR __builtin_amdgcn_s_barrier()
;     __host__ __device__ bool next(int i, Unit& u) const {
;         const long L = (long)i * G + c; if (L >= nwg) return false;
;         int wgid = (int)L; { const int q = nwg / NXCD, r = nwg % NXCD, xcd = wgid % NXCD, off = wgid / NXCD; wgid = (xcd < r ? xcd * (q + 1) : r * (q + 1) + (xcd - r) * q) + off; }
;         const int nig = WGM * nN, gid = wgid / nig, fm = gid * WGM, gsz = (nM - fm) < WGM ? (nM - fm) : WGM;
;         u.pm = fm + ((wgid % nig) % gsz); u.pn = (wgid % nig) / gsz; return true;
;     }
; template <class Epi, class Sched, bool ALIGN_EPI = false, bool SP2 = false>
; __device__ __forceinline__ void gemm_phase(PG8_LAS unsigned char* lds, const Gemm g, const Sched& S, const Epi& E) {
;     ...
;         const bool has_next = S.next(ui + 1, nxt);
;         const char* nA = has_next ? (const char*)g.A + (size_t)nxt.pm * tstepA : cA; const char* nB = has_next ? (const char*)g.Bt + (size_t)nxt.pn * tstepB : cB;
;         for (int t = 0; t < nt; t += 2) {
;             const bool last = (t == nt - 2);
;             const char* a1 = cA + (size_t)(t + 1) * kstep;
;             const char* a2 = last ? nA : cA + (size_t)(t + 2) * kstep; const char* b2 = last ? nB : cB + (size_t)(t + 2) * kstep;
;             const char* a3 = a2 + kstep; const char* b3 = b2 + kstep;
;             if (last && has_next) S.a_ready(nxt);
;             if constexpr (SP2) {
;             PG8_LDB(B0, 0, 0); PG8_LDB(B1, 0, 1); PG8_SCHED; PG8_LDA(At, 0, 0); PG8_STAGE(PG8_SA(1, 1), a1 + hstepA, voffA);
;             PG8_WAIT_V(8); PG8_WAIT_L(0); PG8_BAR; PG8_MMA(0, 0, At, B0); PG8_MMA(0, 1, At, B1); PG8_BAR; PG8_SCHED;
.LBB0_441:
.LBB0_443:
	s_mov_b64 s[86:87], s[66:67]
	s_mov_b64 s[88:89], s[64:65]
	s_add_u32 s76, s64, 0x100
	s_addc_u32 s77, s65, 0
	s_add_u32 s64, s66, 0x40080
	s_addc_u32 s65, s67, 0
	s_mov_b32 s78, -2
	s_add_u32 s50, s64, 0xfffc0080
	s_addc_u32 s51, s65, -1
	s_add_i32 s79, 0, 0x10000
	s_cmp_eq_u32 s78, 12
	s_cselect_b32 s69, s21, s51
	s_cselect_b32 s68, s74, s50
	s_cselect_b32 s67, s15, s77
	s_cselect_b32 s66, s75, s76
	s_add_i32 s80, 0, 0x14000
	v_add_u32_e32 v156, s79, v143
	v_add_u32_e32 v160, s80, v143
	ds_read_b128 v[138:141], v156
	ds_read_b128 v[148:151], v156 offset:1024
	ds_read_b128 v[152:155], v156 offset:2048
	ds_read_b128 v[156:159], v156 offset:3072
	ds_read_b128 v[188:191], v160
	ds_read_b128 v[192:195], v160 offset:1024
	ds_read_b128 v[196:199], v160 offset:2048
	ds_read_b128 v[200:203], v160 offset:3072
	v_lshl_add_u64 v[160:161], s[64:65], 0, v[136:137]
	s_add_i32 m0, s19, 0xc000
	ds_read_b128 v[204:207], v147
	ds_read_b128 v[208:211], v147 offset:1024
	ds_read_b128 v[212:215], v147 offset:2048
	ds_read_b128 v[216:219], v147 offset:3072
	ds_read_b128 v[220:223], v147 offset:4096
	ds_read_b128 v[224:227], v147 offset:5120
	ds_read_b128 v[228:231], v147 offset:6144
	ds_read_b128 v[232:235], v147 offset:7168
	global_load_lds_dwordx4 v[160:161], off
	v_lshl_add_u64 v[160:161], s[64:65], 0, v[134:135]
	s_add_i32 m0, s19, 0xe000
	s_nop 0
	global_load_lds_dwordx4 v[160:161], off
	s_waitcnt vmcnt(8)
	s_waitcnt lgkmcnt(0)
	s_barrier
	s_setprio 1
	s_waitcnt lgkmcnt(0)
	v_mfma_f32_16x16x32_bf16 v[124:127], v[138:141], v[204:207], 0
	s_add_i32 s73, s73, 1
	s_mul_i32 s8, s73, s72
	s_mul_hi_u32 s9, s73, s37
	v_mfma_f32_16x16x32_bf16 v[116:119], v[152:155], v[204:207], 0
	s_add_i32 s9, s9, s8
	s_mul_i32 s8, s73, s37
	s_add_u32 s22, s8, s4
	v_mfma_f32_16x16x32_bf16 v[108:111], v[138:141], v[212:215], 0
	s_addc_u32 s23, s9, s17
	v_mov_b64_e32 v[0:1], s[34:35]
	v_cmp_lt_i64_e64 s[8:9], s[22:23], v[0:1]
	v_mfma_f32_16x16x32_bf16 v[100:103], v[152:155], v[212:215], 0
	s_ashr_i32 s14, s22, 31
	s_lshr_b32 s14, s14, 29
	s_add_i32 s14, s22, s14
	v_mfma_f32_16x16x32_bf16 v[92:95], v[138:141], v[220:223], 0
	s_ashr_i32 s15, s14, 3
	s_and_b32 s14, s14, -8
	s_sub_i32 s14, s22, s14
	v_mfma_f32_16x16x32_bf16 v[84:87], v[152:155], v[220:223], 0
	s_cmp_lt_i32 s14, 0
	s_cselect_b32 s20, s18, s16
	s_mul_i32 s14, s20, s14
	v_mfma_f32_16x16x32_bf16 v[76:79], v[138:141], v[228:231], 0
	s_add_i32 s14, s14, s15
	s_mul_hi_i32 s15, s14, 0x2e8ba2e9
	s_lshr_b32 s20, s15, 31
	v_mfma_f32_16x16x32_bf16 v[68:71], v[152:155], v[228:231], 0
	s_ashr_i32 s15, s15, 4
	s_add_i32 s15, s15, s20
	s_lshl_b32 s20, s15, 2
	v_mfma_f32_16x16x32_bf16 v[124:127], v[148:151], v[208:211], v[124:127]
	s_sub_i32 s21, s2, s20
	s_min_i32 s21, s21, 4
	s_abs_i32 s22, s21
	v_mfma_f32_16x16x32_bf16 v[116:119], v[156:159], v[208:211], v[116:119]
	v_cvt_f32_u32_e32 v0, s22
	s_sub_i32 s50, 0, s22
	s_mulk_i32 s15, 0x58
	v_mfma_f32_16x16x32_bf16 v[108:111], v[148:151], v[216:219], v[108:111]
	s_sub_i32 s15, s14, s15
	v_rcp_iflag_f32_e32 v0, v0
	s_abs_i32 s14, s15
	v_mfma_f32_16x16x32_bf16 v[100:103], v[156:159], v[216:219], v[100:103]
	s_xor_b32 s23, s15, s21
	s_ashr_i32 s23, s23, 31
	v_mul_f32_e32 v0, 0x4f7ffffe, v0
	v_mfma_f32_16x16x32_bf16 v[92:95], v[148:151], v[224:227], v[92:95]
	v_cvt_u32_f32_e32 v0, v0
	s_nop 0
	v_readfirstlane_b32 s51, v0
	v_mfma_f32_16x16x32_bf16 v[84:87], v[156:159], v[224:227], v[84:87]
	s_mul_i32 s50, s50, s51
	s_mul_hi_u32 s50, s51, s50
	s_add_i32 s51, s51, s50
	v_mfma_f32_16x16x32_bf16 v[76:79], v[148:151], v[232:235], v[76:79]
	s_mul_hi_u32 s50, s14, s51
	s_mul_i32 s51, s50, s22
	s_sub_i32 s14, s14, s51
	v_mfma_f32_16x16x32_bf16 v[68:71], v[156:159], v[232:235], v[68:71]
	s_add_i32 s60, s50, 1
	s_sub_i32 s51, s14, s22
	s_cmp_ge_u32 s14, s22
	s_setprio 0
	s_setprio 1
	v_mfma_f32_16x16x32_bf16 v[120:123], v[188:191], v[204:207], 0
	s_cselect_b32 s50, s60, s50
	s_cselect_b32 s14, s51, s14
	s_add_i32 s51, s50, 1
	v_mfma_f32_16x16x32_bf16 v[112:115], v[196:199], v[204:207], 0
	s_cmp_ge_u32 s14, s22
	s_cselect_b32 s14, s51, s50
	s_xor_b32 s14, s14, s23
	v_mfma_f32_16x16x32_bf16 v[104:107], v[188:191], v[212:215], 0
	s_sub_i32 s14, s14, s23
	s_mul_i32 s21, s14, s21
	s_sub_i32 s15, s15, s21
	v_mfma_f32_16x16x32_bf16 v[96:99], v[196:199], v[212:215], 0
	s_add_i32 s20, s15, s20
	s_ashr_i32 s21, s20, 31
	s_lshl_b64 s[22:23], s[20:21], 19
	v_mfma_f32_16x16x32_bf16 v[88:91], v[188:191], v[220:223], 0
	s_add_u32 s22, s56, s22
	s_addc_u32 s23, s57, s23
	s_and_b64 s[50:51], s[8:9], exec
	v_mfma_f32_16x16x32_bf16 v[80:83], v[196:199], v[220:223], 0
	s_cselect_b32 s21, s23, s87
	s_cselect_b32 s74, s22, s86
	s_ashr_i32 s15, s14, 31
	v_mfma_f32_16x16x32_bf16 v[72:75], v[188:191], v[228:231], 0
	s_lshl_b64 s[50:51], s[14:15], 19
	s_add_u32 s60, s5, s50
	s_addc_u32 s61, s6, s51
	v_mfma_f32_16x16x32_bf16 v[64:67], v[196:199], v[228:231], 0
	s_and_b64 s[50:51], s[8:9], exec
	s_cselect_b32 s15, s61, s89
	s_cselect_b32 s75, s60, s88
	v_mfma_f32_16x16x32_bf16 v[120:123], v[192:195], v[208:211], v[120:123]
	v_mfma_f32_16x16x32_bf16 v[112:115], v[200:203], v[208:211], v[112:115]
	v_mfma_f32_16x16x32_bf16 v[104:107], v[192:195], v[216:219], v[104:107]
	v_mfma_f32_16x16x32_bf16 v[96:99], v[200:203], v[216:219], v[96:99]
	v_mfma_f32_16x16x32_bf16 v[88:91], v[192:195], v[224:227], v[88:91]
	v_mfma_f32_16x16x32_bf16 v[80:83], v[200:203], v[224:227], v[80:83]
	v_mfma_f32_16x16x32_bf16 v[72:75], v[192:195], v[232:235], v[72:75]
	v_mfma_f32_16x16x32_bf16 v[64:67], v[200:203], v[232:235], v[64:67]
	s_setprio 0
	s_barrier
; #define PG8_STAGE(bufoff, gbase, voff) do { _Pragma("unroll") for (int _i = 0; _i < 2; ++_i) \
;         __builtin_amdgcn_global_load_lds((const unsigned*)((const char*)(gbase) + (voff)[_i]), (PG8_LAS unsigned*)(lds + (bufoff) + ldsw + _i * 8192), 16, 0, 0); } while (0)
; #define PG8_LDA(dst, b, h) do { _Pragma("unroll") for (int m = 0; m < 4; ++m) _Pragma("unroll") for (int k = 0; k < 2; ++k) dst[m][k] = *(const PG8_LAS bf16x8*)(lds + PG8_SA(b, h) + aoff + m * 2048 + k * 1024); } while (0)
; #define PG8_LDB(dst, b, h) do { _Pragma("unroll") for (int n = 0; n < 2; ++n) _Pragma("unroll") for (int k = 0; k < 2; ++k) dst[n][k] = *(const PG8_LAS bf16x8*)(lds + PG8_SB(b, h) + boff + n * 2048 + k * 1024); } while (0)
; #define PG8_MMA(ai, bj, At, Bt) do { __builtin_amdgcn_s_setprio(1); _Pragma("unroll") for (int m = 0; m < 4; ++m) _Pragma("unroll") for (int n = 0; n < 2; ++n) _Pragma("unroll") for (int k = 0; k < 2; ++k) \
;         acc[ai][bj][m][n] = __builtin_amdgcn_mfma_f32_16x16x32_bf16(Bt[n][k], At[m][k], acc[ai][bj][m][n], 0, 0, 0); __builtin_amdgcn_s_setprio(0); } while (0)
; #define PG8_WAIT_V(n) asm volatile("s_waitcnt vmcnt(" #n ")" ::: "memory")
; #define PG8_WAIT_L(n) asm volatile("s_waitcnt lgkmcnt(" #n ")" ::: "memory")
; #define PG8_BAR __builtin_amdgcn_s_barrier()
; #define PG8_SCHED __builtin_amdgcn_sched_barrier(0)
; template <class Epi, class Sched, bool ALIGN_EPI = false, bool SP2 = false>
; __device__ __forceinline__ void gemm_phase(PG8_LAS unsigned char* lds, const Gemm g, const Sched& S, const Epi& E) {
;     ...
;             PG8_LDA(At, 0, 1); PG8_STAGE(PG8_SB(0, 0), b2, voffB); PG8_STAGE(PG8_SB(0, 1), b2 + hstepB, voffB); PG8_STAGE(PG8_SA(0, 0), a2, voffA);
;             PG8_WAIT_V(8); PG8_WAIT_L(0); PG8_BAR; PG8_MMA(1, 0, At, B0); PG8_MMA(1, 1, At, B1); PG8_BAR; PG8_SCHED;
;             PG8_LDB(B0, 1, 0); PG8_LDB(B1, 1, 1); PG8_SCHED; PG8_LDA(At, 1, 0); PG8_STAGE(PG8_SA(0, 1), a2 + hstepA, voffA);
;             PG8_WAIT_V(8); PG8_WAIT_L(0); PG8_BAR; PG8_MMA(0, 0, At, B0); PG8_MMA(0, 1, At, B1); PG8_BAR; PG8_SCHED;
	s_add_i32 s50, s79, s7
	v_lshl_add_u64 v[160:161], s[66:67], 0, v[144:145]
	s_mov_b32 m0, s50
	ds_read_b128 v[204:207], v147 offset:16384
	ds_read_b128 v[208:211], v147 offset:17408
	ds_read_b128 v[212:215], v147 offset:18432
	ds_read_b128 v[216:219], v147 offset:19456
	ds_read_b128 v[220:223], v147 offset:20480
	ds_read_b128 v[224:227], v147 offset:21504
	ds_read_b128 v[228:231], v147 offset:22528
	ds_read_b128 v[232:235], v147 offset:23552
	global_load_lds_dwordx4 v[160:161], off
	s_add_i32 m0, s50, 0x2000
	s_add_u32 s50, s66, 0x40000
	v_lshl_add_u64 v[174:175], s[66:67], 0, v[128:129]
	s_addc_u32 s51, s67, 0
	s_add_i32 s79, s80, s7
	global_load_lds_dwordx4 v[174:175], off
	v_lshl_add_u64 v[236:237], s[50:51], 0, v[144:145]
	s_mov_b32 m0, s79
	v_lshl_add_u64 v[238:239], s[68:69], 0, v[130:131]
	global_load_lds_dwordx4 v[236:237], off
	v_lshl_add_u64 v[236:237], s[50:51], 0, v[128:129]
	s_add_i32 m0, s79, 0x2000
	s_nop 0
	global_load_lds_dwordx4 v[236:237], off
	v_lshl_add_u64 v[236:237], s[68:69], 0, v[132:133]
	s_mov_b32 m0, s19
	s_nop 0
	global_load_lds_dwordx4 v[236:237], off
	s_mov_b32 m0, s24
	s_nop 0
	global_load_lds_dwordx4 v[238:239], off
	s_waitcnt vmcnt(8)
	s_waitcnt lgkmcnt(0)
	s_barrier
	s_setprio 1
	s_waitcnt lgkmcnt(0)
	v_mfma_f32_16x16x32_bf16 v[60:63], v[138:141], v[204:207], 0
	v_mfma_f32_16x16x32_bf16 v[52:55], v[152:155], v[204:207], 0
	v_mfma_f32_16x16x32_bf16 v[44:47], v[138:141], v[212:215], 0
	v_mfma_f32_16x16x32_bf16 v[36:39], v[152:155], v[212:215], 0
	v_mfma_f32_16x16x32_bf16 v[28:31], v[138:141], v[220:223], 0
	v_mfma_f32_16x16x32_bf16 v[20:23], v[152:155], v[220:223], 0
	v_mfma_f32_16x16x32_bf16 v[12:15], v[138:141], v[228:231], 0
	v_mfma_f32_16x16x32_bf16 v[4:7], v[152:155], v[228:231], 0
	v_mfma_f32_16x16x32_bf16 v[60:63], v[148:151], v[208:211], v[60:63]
	v_mfma_f32_16x16x32_bf16 v[52:55], v[156:159], v[208:211], v[52:55]
	v_mfma_f32_16x16x32_bf16 v[44:47], v[148:151], v[216:219], v[44:47]
	v_mfma_f32_16x16x32_bf16 v[36:39], v[156:159], v[216:219], v[36:39]
	v_mfma_f32_16x16x32_bf16 v[28:31], v[148:151], v[224:227], v[28:31]
	v_mfma_f32_16x16x32_bf16 v[20:23], v[156:159], v[224:227], v[20:23]
	v_mfma_f32_16x16x32_bf16 v[12:15], v[148:151], v[232:235], v[12:15]
	v_mfma_f32_16x16x32_bf16 v[4:7], v[156:159], v[232:235], v[4:7]
	s_setprio 0
	s_setprio 1
	v_mfma_f32_16x16x32_bf16 v[56:59], v[188:191], v[204:207], 0
	v_mfma_f32_16x16x32_bf16 v[48:51], v[196:199], v[204:207], 0
	v_mfma_f32_16x16x32_bf16 v[40:43], v[188:191], v[212:215], 0
	v_mfma_f32_16x16x32_bf16 v[32:35], v[196:199], v[212:215], 0
	v_mfma_f32_16x16x32_bf16 v[24:27], v[188:191], v[220:223], 0
	v_mfma_f32_16x16x32_bf16 v[16:19], v[196:199], v[220:223], 0
	v_mfma_f32_16x16x32_bf16 v[8:11], v[188:191], v[228:231], 0
	v_mfma_f32_16x16x32_bf16 v[0:3], v[196:199], v[228:231], 0
	v_mfma_f32_16x16x32_bf16 v[56:59], v[192:195], v[208:211], v[56:59]
	v_mfma_f32_16x16x32_bf16 v[48:51], v[200:203], v[208:211], v[48:51]
	v_mfma_f32_16x16x32_bf16 v[40:43], v[192:195], v[216:219], v[40:43]
	v_mfma_f32_16x16x32_bf16 v[32:35], v[200:203], v[216:219], v[32:35]
	v_mfma_f32_16x16x32_bf16 v[24:27], v[192:195], v[224:227], v[24:27]
	v_mfma_f32_16x16x32_bf16 v[16:19], v[200:203], v[224:227], v[16:19]
	v_mfma_f32_16x16x32_bf16 v[8:11], v[192:195], v[232:235], v[8:11]
	v_mfma_f32_16x16x32_bf16 v[0:3], v[200:203], v[232:235], v[0:3]
	s_setprio 0
	s_barrier
	s_add_i32 s79, 0, 0x18000
	s_add_i32 s80, 0, 0x1c000
	v_add_u32_e32 v156, s79, v143
	v_add_u32_e32 v162, s80, v143
	ds_read_b128 v[138:141], v156
	ds_read_b128 v[148:151], v156 offset:1024
	ds_read_b128 v[152:155], v156 offset:2048
	ds_read_b128 v[156:159], v156 offset:3072
	ds_read_b128 v[188:191], v162
	ds_read_b128 v[192:195], v162 offset:1024
	ds_read_b128 v[196:199], v162 offset:2048
	ds_read_b128 v[200:203], v162 offset:3072
	s_add_u32 s50, s68, 0x40000
	s_addc_u32 s51, s69, 0
	s_mov_b32 m0, s25
	v_lshl_add_u64 v[240:241], s[50:51], 0, v[132:133]
	ds_read_b128 v[204:207], v147 offset:32768
	ds_read_b128 v[208:211], v147 offset:33792
	ds_read_b128 v[212:215], v147 offset:34816
	ds_read_b128 v[216:219], v147 offset:35840
	ds_read_b128 v[220:223], v147 offset:36864
	ds_read_b128 v[224:227], v147 offset:37888
	ds_read_b128 v[228:231], v147 offset:38912
	ds_read_b128 v[232:235], v147 offset:39936
	global_load_lds_dwordx4 v[240:241], off
	v_lshl_add_u64 v[240:241], s[50:51], 0, v[130:131]
	s_mov_b32 m0, s31
	s_nop 0
	global_load_lds_dwordx4 v[240:241], off
	s_waitcnt vmcnt(8)
	s_waitcnt lgkmcnt(0)
	s_barrier
; #define PG8_STAGE(bufoff, gbase, voff) do { _Pragma("unroll") for (int _i = 0; _i < 2; ++_i) \
;         __builtin_amdgcn_global_load_lds((const unsigned*)((const char*)(gbase) + (voff)[_i]), (PG8_LAS unsigned*)(lds + (bufoff) + ldsw + _i * 8192), 16, 0, 0); } while (0)
; #define PG8_LDA(dst, b, h) do { _Pragma("unroll") for (int m = 0; m < 4; ++m) _Pragma("unroll") for (int k = 0; k < 2; ++k) dst[m][k] = *(const PG8_LAS bf16x8*)(lds + PG8_SA(b, h) + aoff + m * 2048 + k * 1024); } while (0)
; #define PG8_MMA(ai, bj, At, Bt) do { __builtin_amdgcn_s_setprio(1); _Pragma("unroll") for (int m = 0; m < 4; ++m) _Pragma("unroll") for (int n = 0; n < 2; ++n) _Pragma("unroll") for (int k = 0; k < 2; ++k) \
;         acc[ai][bj][m][n] = __builtin_amdgcn_mfma_f32_16x16x32_bf16(Bt[n][k], At[m][k], acc[ai][bj][m][n], 0, 0, 0); __builtin_amdgcn_s_setprio(0); } while (0)
; #define PG8_WAIT_V(n) asm volatile("s_waitcnt vmcnt(" #n ")" ::: "memory")
; #define PG8_WAIT_L(n) asm volatile("s_waitcnt lgkmcnt(" #n ")" ::: "memory")
; #define PG8_BAR __builtin_amdgcn_s_barrier()
; #define PG8_SCHED __builtin_amdgcn_sched_barrier(0)
; template <class Epi, class Sched, bool ALIGN_EPI = false, bool SP2 = false>
; __device__ __forceinline__ void gemm_phase(PG8_LAS unsigned char* lds, const Gemm g, const Sched& S, const Epi& E) {
;     ...
;             PG8_WAIT_V(8); PG8_WAIT_L(0); PG8_BAR; PG8_MMA(0, 0, At, B0); PG8_MMA(0, 1, At, B1); PG8_BAR; PG8_SCHED;
;             PG8_LDA(At, 1, 1); PG8_STAGE(PG8_SB(1, 0), b3, voffB); PG8_STAGE(PG8_SB(1, 1), b3 + hstepB, voffB); PG8_STAGE(PG8_SA(1, 0), a3, voffA);
;             PG8_WAIT_V(8); PG8_WAIT_L(0); PG8_BAR; PG8_MMA(1, 0, At, B0); PG8_MMA(1, 1, At, B1); PG8_BAR; PG8_SCHED;
	s_setprio 1
	s_waitcnt lgkmcnt(0)
	v_mfma_f32_16x16x32_bf16 v[124:127], v[138:141], v[204:207], v[124:127]
	v_mfma_f32_16x16x32_bf16 v[116:119], v[152:155], v[204:207], v[116:119]
	v_mfma_f32_16x16x32_bf16 v[108:111], v[138:141], v[212:215], v[108:111]
	v_mfma_f32_16x16x32_bf16 v[100:103], v[152:155], v[212:215], v[100:103]
	v_mfma_f32_16x16x32_bf16 v[92:95], v[138:141], v[220:223], v[92:95]
	v_mfma_f32_16x16x32_bf16 v[84:87], v[152:155], v[220:223], v[84:87]
	v_mfma_f32_16x16x32_bf16 v[76:79], v[138:141], v[228:231], v[76:79]
	v_mfma_f32_16x16x32_bf16 v[68:71], v[152:155], v[228:231], v[68:71]
	v_mfma_f32_16x16x32_bf16 v[124:127], v[148:151], v[208:211], v[124:127]
	v_mfma_f32_16x16x32_bf16 v[116:119], v[156:159], v[208:211], v[116:119]
	v_mfma_f32_16x16x32_bf16 v[108:111], v[148:151], v[216:219], v[108:111]
	v_mfma_f32_16x16x32_bf16 v[100:103], v[156:159], v[216:219], v[100:103]
	v_mfma_f32_16x16x32_bf16 v[92:95], v[148:151], v[224:227], v[92:95]
	v_mfma_f32_16x16x32_bf16 v[84:87], v[156:159], v[224:227], v[84:87]
	v_mfma_f32_16x16x32_bf16 v[76:79], v[148:151], v[232:235], v[76:79]
	v_mfma_f32_16x16x32_bf16 v[68:71], v[156:159], v[232:235], v[68:71]
	s_setprio 0
	s_setprio 1
	v_mfma_f32_16x16x32_bf16 v[120:123], v[188:191], v[204:207], v[120:123]
	v_mfma_f32_16x16x32_bf16 v[112:115], v[196:199], v[204:207], v[112:115]
	v_mfma_f32_16x16x32_bf16 v[104:107], v[188:191], v[212:215], v[104:107]
	v_mfma_f32_16x16x32_bf16 v[96:99], v[196:199], v[212:215], v[96:99]
	v_mfma_f32_16x16x32_bf16 v[88:91], v[188:191], v[220:223], v[88:91]
	v_mfma_f32_16x16x32_bf16 v[80:83], v[196:199], v[220:223], v[80:83]
	v_mfma_f32_16x16x32_bf16 v[72:75], v[188:191], v[228:231], v[72:75]
	v_mfma_f32_16x16x32_bf16 v[64:67], v[196:199], v[228:231], v[64:67]
	v_mfma_f32_16x16x32_bf16 v[120:123], v[192:195], v[208:211], v[120:123]
	v_mfma_f32_16x16x32_bf16 v[112:115], v[200:203], v[208:211], v[112:115]
	v_mfma_f32_16x16x32_bf16 v[104:107], v[192:195], v[216:219], v[104:107]
	v_mfma_f32_16x16x32_bf16 v[96:99], v[200:203], v[216:219], v[96:99]
	v_mfma_f32_16x16x32_bf16 v[88:91], v[192:195], v[224:227], v[88:91]
	v_mfma_f32_16x16x32_bf16 v[80:83], v[200:203], v[224:227], v[80:83]
	v_mfma_f32_16x16x32_bf16 v[72:75], v[192:195], v[232:235], v[72:75]
	v_mfma_f32_16x16x32_bf16 v[64:67], v[200:203], v[232:235], v[64:67]
	s_setprio 0
	s_barrier
	s_add_i32 s50, s79, s7
	v_lshl_add_u64 v[160:161], v[160:161], 0, s[48:49]
	s_mov_b32 m0, s50
	ds_read_b128 v[204:207], v147 offset:49152
	ds_read_b128 v[208:211], v147 offset:50176
	ds_read_b128 v[212:215], v147 offset:51200
	ds_read_b128 v[216:219], v147 offset:52224
	ds_read_b128 v[220:223], v147 offset:53248
	ds_read_b128 v[224:227], v147 offset:54272
	ds_read_b128 v[228:231], v147 offset:55296
	ds_read_b128 v[232:235], v147 offset:56320
	global_load_lds_dwordx4 v[160:161], off
	s_add_i32 m0, s50, 0x2000
	s_add_u32 s50, s66, 0x40080
	v_lshl_add_u64 v[160:161], v[174:175], 0, s[48:49]
	s_addc_u32 s51, s67, 0
	s_add_i32 s66, s80, s7
	global_load_lds_dwordx4 v[160:161], off
	v_lshl_add_u64 v[160:161], s[50:51], 0, v[144:145]
	s_mov_b32 m0, s66
	s_nop 0
	global_load_lds_dwordx4 v[160:161], off
	v_lshl_add_u64 v[160:161], s[50:51], 0, v[128:129]
	s_add_i32 m0, s66, 0x2000
	s_nop 0
	global_load_lds_dwordx4 v[160:161], off
	v_lshl_add_u64 v[160:161], v[236:237], 0, s[48:49]
	s_mov_b32 m0, s70
	s_nop 0
	global_load_lds_dwordx4 v[160:161], off
	v_lshl_add_u64 v[160:161], v[238:239], 0, s[48:49]
	s_mov_b32 m0, s71
	s_nop 0
	global_load_lds_dwordx4 v[160:161], off
	s_waitcnt vmcnt(8)
	s_waitcnt lgkmcnt(0)
	s_barrier
	s_setprio 1
	s_waitcnt lgkmcnt(0)
	v_mfma_f32_16x16x32_bf16 v[60:63], v[138:141], v[204:207], v[60:63]
	v_mfma_f32_16x16x32_bf16 v[52:55], v[152:155], v[204:207], v[52:55]
	v_mfma_f32_16x16x32_bf16 v[44:47], v[138:141], v[212:215], v[44:47]
	v_mfma_f32_16x16x32_bf16 v[36:39], v[152:155], v[212:215], v[36:39]
	v_mfma_f32_16x16x32_bf16 v[28:31], v[138:141], v[220:223], v[28:31]
	v_mfma_f32_16x16x32_bf16 v[20:23], v[152:155], v[220:223], v[20:23]
	v_mfma_f32_16x16x32_bf16 v[12:15], v[138:141], v[228:231], v[12:15]
	v_mfma_f32_16x16x32_bf16 v[4:7], v[152:155], v[228:231], v[4:7]
	v_mfma_f32_16x16x32_bf16 v[60:63], v[148:151], v[208:211], v[60:63]
	v_mfma_f32_16x16x32_bf16 v[52:55], v[156:159], v[208:211], v[52:55]
	v_mfma_f32_16x16x32_bf16 v[44:47], v[148:151], v[216:219], v[44:47]
	v_mfma_f32_16x16x32_bf16 v[36:39], v[156:159], v[216:219], v[36:39]
	v_mfma_f32_16x16x32_bf16 v[28:31], v[148:151], v[224:227], v[28:31]
	v_mfma_f32_16x16x32_bf16 v[20:23], v[156:159], v[224:227], v[20:23]
	v_mfma_f32_16x16x32_bf16 v[12:15], v[148:151], v[232:235], v[12:15]
	v_mfma_f32_16x16x32_bf16 v[4:7], v[156:159], v[232:235], v[4:7]
	s_setprio 0
	s_setprio 1
	v_mfma_f32_16x16x32_bf16 v[56:59], v[188:191], v[204:207], v[56:59]
	v_mfma_f32_16x16x32_bf16 v[48:51], v[196:199], v[204:207], v[48:51]
	v_mfma_f32_16x16x32_bf16 v[40:43], v[188:191], v[212:215], v[40:43]
	v_mfma_f32_16x16x32_bf16 v[32:35], v[196:199], v[212:215], v[32:35]
	v_mfma_f32_16x16x32_bf16 v[24:27], v[188:191], v[220:223], v[24:27]
	v_mfma_f32_16x16x32_bf16 v[16:19], v[196:199], v[220:223], v[16:19]
	v_mfma_f32_16x16x32_bf16 v[8:11], v[188:191], v[228:231], v[8:11]
	v_mfma_f32_16x16x32_bf16 v[0:3], v[196:199], v[228:231], v[0:3]
	v_mfma_f32_16x16x32_bf16 v[56:59], v[192:195], v[208:211], v[56:59]
	v_mfma_f32_16x16x32_bf16 v[48:51], v[200:203], v[208:211], v[48:51]
	v_mfma_f32_16x16x32_bf16 v[40:43], v[192:195], v[216:219], v[40:43]
	v_mfma_f32_16x16x32_bf16 v[32:35], v[200:203], v[216:219], v[32:35]
	v_mfma_f32_16x16x32_bf16 v[24:27], v[192:195], v[224:227], v[24:27]
	v_mfma_f32_16x16x32_bf16 v[16:19], v[200:203], v[224:227], v[16:19]
	v_mfma_f32_16x16x32_bf16 v[8:11], v[192:195], v[232:235], v[8:11]
	v_mfma_f32_16x16x32_bf16 v[0:3], v[200:203], v[232:235], v[0:3]
	s_setprio 0
	s_barrier
	s_add_i32 s78, s78, 2
	s_add_u32 s76, s76, 0x100
	s_addc_u32 s77, s77, 0
	s_add_u32 s64, s64, 0x100
	s_addc_u32 s65, s65, 0
